# P0 rmsnorm loop: norm gain loads hoisted out of the row loop (3 store-serialised round trips per row removed); P7 final-norm loop: both half-row loads issued up front, gain hoisted
# speedup vs baseline: 1.0039x; 1.0039x over previous
; __device__ __forceinline__ void p0_prep(const Ctx& c, LAS unsigned char* lds, int vcu, int G, int wave_s) {
;     ...
;     bf16* XN = (bf16*)(ws + WS_XN);
;     for (int m = gw; m < R_ALL; m += NGW) {
;         unsigned long long* o8 = (unsigned long long*)(XN + (size_t)m * D) + lane;
;         if (m >= ROW_M0 + 16) {
; #pragma unroll
;             for (int j = 0; j < 4; ++j) o8[64 * j] = 0ull;
;             continue; }
;         const float* src = m < ROW_S0 ? c.x_prompt + (size_t)m * D : (m < ROW_M0 ? c.x_sample + (size_t)(m - ROW_S0) * D : c.meta + (size_t)(m - ROW_M0) * D);
;         const f32x4* xr = (const f32x4*)src + lane; const f32x4* gr = (const f32x4*)c.n1g + lane;
;         f32x4 v[4]; float s = 0.f;
.LBB0_30:
	s_cmp_gt_i32 s12, 0x81ff
	v_mbcnt_lo_u32_b32 v182, -1, 0
	s_cbranch_scc1 .LBB0_42
	v_readlane_b32 s0, v255, 2
	s_ashr_i32 s1, s13, 31
	s_ashr_i32 s2, s0, 31
	s_add_u32 s0, s13, s0
	s_addc_u32 s1, s1, s2
	s_lshl_b64 s[2:3], s[0:1], 12
	s_waitcnt lgkmcnt(0)
	s_add_u32 s2, s36, s2
	s_addc_u32 s3, s37, s3
	s_ashr_i32 s71, s70, 31
	s_lshl_b64 s[4:5], s[70:71], 12
	s_lshl_b64 s[0:1], s[0:1], 11
	v_mov_b32_e32 v7, 0
	v_lshlrev_b32_e32 v6, 4, v2
	s_add_u32 s0, s34, s0
	v_lshl_add_u64 v[4:5], s[50:51], 0, v[6:7]
	v_lshlrev_b32_e32 v6, 3, v2
	s_addc_u32 s1, s35, s1
	v_mbcnt_hi_u32_b32 v13, -1, v182
	v_lshl_add_u64 v[6:7], s[0:1], 0, v[6:7]
	s_mov_b64 s[0:1], 0x3400400
	v_and_b32_e32 v8, 64, v13
	v_lshl_add_u64 v[6:7], v[6:7], 0, s[0:1]
	s_lshl_b64 s[6:7], s[70:71], 11
	s_mov_b32 s8, 0
	v_lshlrev_b32_e32 v10, 4, v2
	v_mov_b32_e32 v11, 0x358637bd
	s_mov_b32 s13, 0xf800000
	v_mov_b32_e32 v12, 0x260
	v_add_u32_e32 v14, 64, v8
	v_xor_b32_e32 v15, 1, v13
	v_xor_b32_e32 v16, 2, v13
	v_xor_b32_e32 v17, 4, v13
	v_xor_b32_e32 v18, 8, v13
	v_xor_b32_e32 v19, 16, v13
	v_xor_b32_e32 v20, 32, v13
	global_load_dwordx4 v[100:103], v[4:5], off
	global_load_dwordx4 v[104:107], v[4:5], off offset:1024
	global_load_dwordx4 v[108:111], v[4:5], off offset:2048
	global_load_dwordx4 v[112:115], v[4:5], off offset:3072
	s_branch .LBB0_33

; __device__ __forceinline__ unsigned cvt_pk_bf16(float lo, float hi) { unsigned r; asm volatile("v_cvt_pk_bf16_f32 %0, %1, %2" : "=v"(r) : "v"(lo), "v"(hi)); return r; }
; __device__ __forceinline__ void p0_prep(const Ctx& c, LAS unsigned char* lds, int vcu, int G, int wave_s) {
;     ...
;         f32x4 v[4]; float s = 0.f;
; #pragma unroll
;         for (int j = 0; j < 4; ++j) { v[j] = __builtin_nontemporal_load(xr + 64 * j); s += (v[j].x * v[j].x + v[j].y * v[j].y) + (v[j].z * v[j].z + v[j].w * v[j].w); }
;         const float rstd = 1.f / sqrtf(wave_sum(s) * (1.f / D) + 1e-6f);
; #pragma unroll
;         for (int j = 0; j < 4; ++j) { const f32x4 g = gr[64 * j]; const f32x4 y = v[j] * rstd * g;
;             o8[64 * j] = (unsigned long long)cvt_pk_bf16(y.x, y.y) | ((unsigned long long)cvt_pk_bf16(y.z, y.w) << 32); }
.LBB0_39:
	global_load_dwordx4 v[22:25], v10, s[0:1] nt
	global_load_dwordx4 v[26:29], v10, s[0:1] offset:1024 nt
	global_load_dwordx4 v[30:33], v10, s[0:1] offset:3072 nt
	global_load_dwordx4 v[34:37], v10, s[0:1] offset:2048 nt
	v_cmp_lt_i32_e32 vcc, v15, v14
	s_waitcnt vmcnt(3)
	v_pk_mul_f32 v[42:43], v[22:23], v[22:23]
	v_cndmask_b32_e32 v8, v13, v15, vcc
	v_lshlrev_b32_e32 v21, 2, v8
	v_pk_mul_f32 v[8:9], v[24:25], v[24:25]
	s_waitcnt vmcnt(2)
	v_pk_mul_f32 v[44:45], v[28:29], v[28:29]
	v_pk_mul_f32 v[46:47], v[26:27], v[26:27]
	v_pk_mov_b32 v[52:53], v[42:43], v[8:9] op_sel:[1,0]
	v_mov_b32_e32 v43, v9
	v_pk_mov_b32 v[8:9], v[46:47], v[44:45] op_sel:[1,0]
	v_mov_b32_e32 v47, v45
	s_waitcnt vmcnt(1)
	v_mul_f32_e32 v51, v30, v30
	s_waitcnt vmcnt(0)
	v_mul_f32_e32 v48, v35, v35
	v_mul_f32_e32 v50, v37, v37
	v_pk_add_f32 v[42:43], v[52:53], v[42:43]
	v_pk_add_f32 v[8:9], v[8:9], v[46:47]
	v_mul_f32_e32 v54, v31, v31
	v_mul_f32_e32 v55, v32, v32
	v_mul_f32_e32 v56, v33, v33
	v_pk_fma_f32 v[44:45], v[34:35], v[34:35], v[48:49] op_sel_hi:[1,1,0]
	v_pk_fma_f32 v[48:49], v[36:37], v[36:37], v[50:51] op_sel_hi:[1,1,0]
	v_pk_add_f32 v[42:43], v[42:43], v[42:43] op_sel:[0,1] op_sel_hi:[1,0]
	v_pk_add_f32 v[8:9], v[8:9], v[8:9] op_sel:[0,1] op_sel_hi:[1,0]
	v_mov_b32_e32 v45, v55
	v_mov_b32_e32 v49, v56
	v_mov_b32_e32 v43, v51
	v_mov_b32_e32 v9, v54
	v_pk_add_f32 v[44:45], v[44:45], v[48:49]
	v_pk_add_f32 v[8:9], v[42:43], v[8:9]
	v_cmp_lt_i32_e32 vcc, v16, v14
	v_pk_add_f32 v[8:9], v[8:9], v[44:45]
	s_nop 0
	v_add_f32_e32 v8, v8, v9
	ds_bpermute_b32 v9, v21, v8
	v_cndmask_b32_e32 v21, v13, v16, vcc
	v_lshlrev_b32_e32 v21, 2, v21
	v_cmp_lt_i32_e32 vcc, v17, v14
	s_waitcnt lgkmcnt(0)
	v_add_f32_e32 v8, v8, v9
	ds_bpermute_b32 v9, v21, v8
	v_cndmask_b32_e32 v21, v13, v17, vcc
	v_lshlrev_b32_e32 v21, 2, v21
	v_cmp_lt_i32_e32 vcc, v18, v14
	s_waitcnt lgkmcnt(0)
	v_add_f32_e32 v8, v8, v9
	ds_bpermute_b32 v9, v21, v8
	v_cndmask_b32_e32 v21, v13, v18, vcc
	v_lshlrev_b32_e32 v21, 2, v21
	v_cmp_lt_i32_e32 vcc, v19, v14
	s_waitcnt lgkmcnt(0)
	v_add_f32_e32 v8, v8, v9
	ds_bpermute_b32 v9, v21, v8
	v_cndmask_b32_e32 v21, v13, v19, vcc
	v_lshlrev_b32_e32 v21, 2, v21
	v_cmp_lt_i32_e32 vcc, v20, v14
	s_waitcnt lgkmcnt(0)
	v_add_f32_e32 v8, v8, v9
	ds_bpermute_b32 v9, v21, v8
	v_cndmask_b32_e32 v21, v13, v20, vcc
	v_lshlrev_b32_e32 v21, 2, v21
	s_waitcnt lgkmcnt(0)
	v_add_f32_e32 v8, v8, v9
	ds_bpermute_b32 v9, v21, v8
	s_waitcnt lgkmcnt(0)
	v_add_f32_e32 v8, v8, v9
	v_fmamk_f32 v8, v8, 0x3a800000, v11
	v_mul_f32_e32 v9, 0x4f800000, v8
	v_cmp_gt_f32_e32 vcc, s13, v8
	s_nop 1
	v_cndmask_b32_e32 v8, v8, v9, vcc
	v_sqrt_f32_e32 v9, v8
	s_nop 0
	v_add_u32_e32 v21, -1, v9
	v_add_u32_e32 v42, 1, v9
	v_fma_f32 v43, -v21, v9, v8
	v_fma_f32 v44, -v42, v9, v8
	v_cmp_ge_f32_e64 s[0:1], 0, v43
	s_nop 1
	v_cndmask_b32_e64 v9, v9, v21, s[0:1]
	v_cmp_lt_f32_e64 s[0:1], 0, v44
	s_nop 1
	v_cndmask_b32_e64 v9, v9, v42, s[0:1]
	v_mul_f32_e32 v21, 0x37800000, v9
	v_cndmask_b32_e32 v9, v9, v21, vcc
	v_cmp_class_f32_e32 vcc, v8, v12
	s_nop 1
	v_cndmask_b32_e32 v8, v9, v8, vcc
	v_div_scale_f32 v9, s[0:1], v8, v8, 1.0
	v_rcp_f32_e32 v21, v9
	v_div_scale_f32 v42, vcc, 1.0, v8, 1.0
	s_mov_b64 s[0:1], 0
	v_fma_f32 v43, -v9, v21, 1.0
	v_fmac_f32_e32 v21, v43, v21
	v_mul_f32_e32 v43, v42, v21
	v_fma_f32 v44, -v9, v43, v42
	v_fmac_f32_e32 v43, v44, v21
	v_fma_f32 v9, -v9, v43, v42
	v_div_fmas_f32 v9, v9, v21, v43
	v_div_fixup_f32 v8, v9, v8, 1.0
	v_pk_mul_f32 v[22:23], v[22:23], v[8:9] op_sel_hi:[1,0]
	v_pk_mul_f32 v[24:25], v[24:25], v[8:9] op_sel_hi:[1,0]
	v_pk_mul_f32 v[22:23], v[100:101], v[22:23]
	v_pk_mul_f32 v[24:25], v[102:103], v[24:25]
	v_cvt_pk_bf16_f32 v22, v22, v23
	v_pk_mul_f32 v[26:27], v[26:27], v[8:9] op_sel_hi:[1,0]
	v_cvt_pk_bf16_f32 v23, v24, v25
	global_store_dwordx2 v[6:7], v[22:23], off offset:-1024
	v_pk_mul_f32 v[28:29], v[28:29], v[8:9] op_sel_hi:[1,0]
	s_nop 0
	v_pk_mul_f32 v[22:23], v[104:105], v[26:27]
	v_pk_mul_f32 v[24:25], v[106:107], v[28:29]
	v_cvt_pk_bf16_f32 v22, v22, v23
	v_pk_mul_f32 v[26:27], v[34:35], v[8:9] op_sel_hi:[1,0]
	v_cvt_pk_bf16_f32 v23, v24, v25
	global_store_dwordx2 v[6:7], v[22:23], off offset:-512
	v_pk_mul_f32 v[28:29], v[36:37], v[8:9] op_sel_hi:[1,0]
	s_nop 0
	v_pk_mul_f32 v[22:23], v[108:109], v[26:27]
	v_pk_mul_f32 v[24:25], v[110:111], v[28:29]
	v_cvt_pk_bf16_f32 v22, v22, v23
	v_pk_mul_f32 v[26:27], v[30:31], v[8:9] op_sel_hi:[1,0]
	v_cvt_pk_bf16_f32 v23, v24, v25
	global_store_dwordx2 v[6:7], v[22:23], off
	v_pk_mul_f32 v[8:9], v[32:33], v[8:9] op_sel_hi:[1,0]
	s_nop 0
	v_pk_mul_f32 v[24:25], v[8:9], v[114:115]
	v_pk_mul_f32 v[8:9], v[26:27], v[112:113]
	s_nop 0
	v_cvt_pk_bf16_f32 v8, v8, v9
	v_cvt_pk_bf16_f32 v9, v24, v25

; __device__ __forceinline__ int fresh_tid(int wave_s) { unsigned m = ~0u; asm volatile("" : "+s"(m)); int t = wave_s * 64 + (int)__builtin_amdgcn_mbcnt_hi(m, __builtin_amdgcn_mbcnt_lo(m, 0u)); asm volatile("" : "+v"(t)); return t; }
; __global__ void __launch_bounds__(512, 2) hybrid_fwd(Ctx c) {
;     ...
;     { const int tid_ = fresh_tid(wave0); const int lane = tid_ & 63, wave = wave0;
;       const int gw = vcu * 8 + wave, NGW = G * 8; const float* SS = (const float*)(ws + WS_SS2); const bf16* H2 = (const bf16*)(ws + WS_H2B);
;       for (int m = gw; m < R_TAIL; m += NGW) { float* y = yrow(c, m);
;           const float part = lane < 16 ? SS[(size_t)m * 16 + lane] : 0.f;
;           const float rstd = 1.f / sqrtf(wave_sum(part) * (1.f / D) + 1e-6f);
;           const u32x4* hr = (const u32x4*)(H2 + (size_t)m * D) + lane; f32x4* yr = (f32x4*)y; const f32x4* gr = (const f32x4*)c.nfg;
; #pragma unroll
;           for (int j = 0; j < 2; ++j) { float hf[8]; unpack8(__builtin_nontemporal_load(hr + 64 * j), hf); const int q = 2 * (64 * j + lane);
;               const f32x4 g0 = gr[q], g1 = gr[q + 1];
;               __builtin_nontemporal_store((f32x4){hf[0], hf[1], hf[2], hf[3]} * rstd * g0, yr + q); __builtin_nontemporal_store((f32x4){hf[4], hf[5], hf[6], hf[7]} * rstd * g1, yr + q + 1); } } }
.LBB0_1421:
	s_or_b64 exec, exec, s[0:1]
	s_mov_b32 s0, -1
	s_waitcnt lgkmcnt(0)
	s_barrier
	s_nop 0
	v_mbcnt_lo_u32_b32 v0, s0, 0
	v_mbcnt_hi_u32_b32 v0, s0, v0
	v_readlane_b32 s0, v255, 2
	s_add_i32 s4, s0, s94
	v_add_u32_e32 v0, s33, v0
	s_cmp_gt_i32 s4, 0x80ff
	s_cbranch_scc1 .LBB0_1426
	v_and_b32_e32 v12, 63, v0
	v_and_b32_e32 v0, 64, v212
	v_add_u32_e32 v0, 64, v0
	v_xor_b32_e32 v1, 1, v212
	v_cmp_lt_i32_e32 vcc, v1, v0
	s_ashr_i32 s5, s4, 31
	v_mov_b32_e32 v5, 0
	v_cndmask_b32_e32 v1, v212, v1, vcc
	v_lshlrev_b32_e32 v6, 2, v1
	v_xor_b32_e32 v1, 2, v212
	v_cmp_lt_i32_e32 vcc, v1, v0
	v_lshlrev_b32_e32 v4, 5, v12
	s_lshl_b64 s[2:3], s[4:5], 11
	v_cndmask_b32_e32 v1, v212, v1, vcc
	v_lshlrev_b32_e32 v7, 2, v1
	v_xor_b32_e32 v1, 4, v212
	v_cmp_lt_i32_e32 vcc, v1, v0
	v_lshl_or_b32 v2, v12, 4, s2
	v_mov_b32_e32 v3, s3
	v_cndmask_b32_e32 v1, v212, v1, vcc
	v_lshlrev_b32_e32 v8, 2, v1
	v_xor_b32_e32 v1, 8, v212
	v_cmp_lt_i32_e32 vcc, v1, v0
	s_lshl_b64 s[2:3], s[4:5], 6
	v_lshlrev_b32_e32 v14, 1, v12
	v_cndmask_b32_e32 v1, v212, v1, vcc
	v_lshlrev_b32_e32 v9, 2, v1
	v_xor_b32_e32 v1, 16, v212
	v_cmp_lt_i32_e32 vcc, v1, v0
	s_ashr_i32 s81, s80, 31
	v_cmp_gt_u32_e64 s[0:1], 16, v12
	v_cndmask_b32_e32 v1, v212, v1, vcc
	v_lshlrev_b32_e32 v10, 2, v1
	v_xor_b32_e32 v1, 32, v212
	v_cmp_lt_i32_e32 vcc, v1, v0
	s_lshl_b64 s[6:7], s[80:81], 11
	s_lshl_b64 s[8:9], s[80:81], 6
	v_cndmask_b32_e32 v0, v212, v1, vcc
	v_lshlrev_b32_e32 v11, 2, v0
	v_lshl_add_u64 v[0:1], s[52:53], 0, v[4:5]
	v_lshlrev_b32_e32 v4, 2, v12
	v_lshl_add_u64 v[4:5], s[2:3], 0, v[4:5]
	s_mov_b64 s[2:3], 0x3000000
	v_lshl_add_u64 v[4:5], v[4:5], 0, s[2:3]
	v_mov_b32_e32 v12, 0x358637bd
	s_mov_b32 s12, 0xf800000
	v_mov_b32_e32 v13, 0x260
	s_mov_b32 s13, 0x17900000
	v_lshlrev_b32_e32 v14, 4, v14
	global_load_dwordx4 v[40:43], v[0:1], off
	global_load_dwordx4 v[44:47], v[0:1], off offset:16
	global_load_dwordx4 v[48:51], v[0:1], off offset:2048
	global_load_dwordx4 v[52:55], v[0:1], off offset:2064
	s_branch .LBB0_1424
.LBB0_1423:
	s_or_b64 exec, exec, s[2:3]
	v_lshl_add_u64 v[16:17], s[34:35], 0, v[2:3]
	v_add_co_u32_e32 v28, vcc, s13, v16
	s_nop 1
	v_addc_co_u32_e32 v29, vcc, 0, v17, vcc
	global_load_dwordx4 v[16:19], v[28:29], off nt
	global_load_dwordx4 v[56:59], v[28:29], off offset:1024 nt
	s_waitcnt vmcnt(2)
	ds_bpermute_b32 v30, v6, v15
	s_waitcnt lgkmcnt(0)
	v_add_f32_e32 v15, v15, v30
	ds_bpermute_b32 v30, v7, v15
	s_add_i32 s2, s4, 0xffff8000
	s_cmp_lt_i32 s4, 0x8000
	s_cselect_b32 s10, 0, 0x8000000
	s_cselect_b32 s3, s5, 0
	s_waitcnt lgkmcnt(0)
	v_add_f32_e32 v15, v15, v30
	ds_bpermute_b32 v30, v8, v15
	s_cselect_b32 s2, s4, s2
	s_add_u32 s14, s54, s10
	s_addc_u32 s15, s55, 0
	s_lshl_b64 s[10:11], s[2:3], 12
	s_waitcnt lgkmcnt(0)
	v_add_f32_e32 v15, v15, v30
	ds_bpermute_b32 v30, v9, v15
	s_add_u32 s10, s14, s10
	s_addc_u32 s11, s15, s11
	s_add_u32 s4, s4, s80
	s_addc_u32 s5, s5, s81
	s_waitcnt lgkmcnt(0)
	v_add_f32_e32 v15, v15, v30
	ds_bpermute_b32 v30, v10, v15
	v_lshl_add_u64 v[2:3], v[2:3], 0, s[6:7]
	s_cmp_gt_i32 s4, 0x80ff
	v_lshl_add_u64 v[4:5], v[4:5], 0, s[8:9]
	s_waitcnt lgkmcnt(0)
	v_add_f32_e32 v15, v15, v30
	ds_bpermute_b32 v30, v11, v15
	s_waitcnt lgkmcnt(0)
	v_add_f32_e32 v15, v15, v30
	v_fmamk_f32 v15, v15, 0x3a800000, v12
	v_mul_f32_e32 v30, 0x4f800000, v15
	v_cmp_gt_f32_e32 vcc, s12, v15
	s_waitcnt vmcnt(1)
	v_and_b32_e32 v35, 0xffff0000, v18
	v_cndmask_b32_e32 v15, v15, v30, vcc
	v_sqrt_f32_e32 v30, v15
	s_nop 0
	v_add_u32_e32 v31, -1, v30
	v_add_u32_e32 v32, 1, v30
	v_fma_f32 v33, -v31, v30, v15
	v_fma_f32 v34, -v32, v30, v15
	v_cmp_ge_f32_e64 s[2:3], 0, v33
	s_nop 1
	v_cndmask_b32_e64 v30, v30, v31, s[2:3]
	v_cmp_lt_f32_e64 s[2:3], 0, v34
	s_nop 1
	v_cndmask_b32_e64 v30, v30, v32, s[2:3]
	v_mul_f32_e32 v31, 0x37800000, v30
	v_cndmask_b32_e32 v30, v30, v31, vcc
	v_cmp_class_f32_e32 vcc, v15, v13
	s_nop 1
	v_cndmask_b32_e32 v15, v30, v15, vcc
	v_div_scale_f32 v30, s[2:3], v15, v15, 1.0
	v_rcp_f32_e32 v31, v30
	v_div_scale_f32 v32, vcc, 1.0, v15, 1.0
	v_fma_f32 v33, -v30, v31, 1.0
	v_fmac_f32_e32 v31, v33, v31
	v_mul_f32_e32 v33, v32, v31
	v_fma_f32 v34, -v30, v33, v32
	v_fmac_f32_e32 v33, v34, v31
	v_fma_f32 v30, -v30, v33, v32
	v_div_fmas_f32 v30, v30, v31, v33
	v_div_fixup_f32 v30, v30, v15, 1.0
	v_lshlrev_b32_e32 v32, 16, v16
	v_and_b32_e32 v33, 0xffff0000, v16
	v_lshlrev_b32_e32 v16, 16, v17
	v_and_b32_e32 v17, 0xffff0000, v17
	v_lshlrev_b32_e32 v34, 16, v18
	v_lshlrev_b32_e32 v18, 16, v19
	v_and_b32_e32 v19, 0xffff0000, v19
	v_pk_mul_f32 v[32:33], v[30:31], v[32:33] op_sel_hi:[0,1]
	v_pk_mul_f32 v[16:17], v[30:31], v[16:17] op_sel_hi:[0,1]
	v_pk_mul_f32 v[34:35], v[30:31], v[34:35] op_sel_hi:[0,1]
	v_pk_mul_f32 v[36:37], v[30:31], v[18:19] op_sel_hi:[0,1]
	s_nop 0
	v_pk_mul_f32 v[18:19], v[42:43], v[16:17]
	v_pk_mul_f32 v[16:17], v[40:41], v[32:33]
	v_pk_mul_f32 v[22:23], v[46:47], v[36:37]
	v_pk_mul_f32 v[20:21], v[44:45], v[34:35]
	global_store_dwordx4 v14, v[16:19], s[10:11] nt
	global_store_dwordx4 v14, v[20:23], s[10:11] offset:16 nt
	s_waitcnt vmcnt(2)
	v_lshlrev_b32_e32 v28, 16, v56
	v_and_b32_e32 v29, 0xffff0000, v56
	v_lshlrev_b32_e32 v56, 16, v57
	v_and_b32_e32 v57, 0xffff0000, v57
	v_lshlrev_b32_e32 v32, 16, v58
	v_and_b32_e32 v33, 0xffff0000, v58
	v_lshlrev_b32_e32 v58, 16, v59
	v_and_b32_e32 v59, 0xffff0000, v59
	v_pk_mul_f32 v[28:29], v[30:31], v[28:29] op_sel_hi:[0,1]
	v_pk_mul_f32 v[56:57], v[30:31], v[56:57] op_sel_hi:[0,1]
	v_pk_mul_f32 v[32:33], v[30:31], v[32:33] op_sel_hi:[0,1]
	v_pk_mul_f32 v[30:31], v[30:31], v[58:59] op_sel_hi:[0,1]
	v_pk_mul_f32 v[18:19], v[50:51], v[56:57]
	v_pk_mul_f32 v[16:17], v[48:49], v[28:29]
	v_pk_mul_f32 v[22:23], v[54:55], v[30:31]
	v_pk_mul_f32 v[20:21], v[52:53], v[32:33]
	global_store_dwordx4 v14, v[16:19], s[10:11] offset:2048 nt
	global_store_dwordx4 v14, v[20:23], s[10:11] offset:2064 nt
	s_cbranch_scc1 .LBB0_1426
